# scan item remap for XCD-local L2 sharing + convert loop load hoisting beside scan
# speedup vs baseline: 1.0112x; 1.0112x over previous
; #define LAS __attribute__((address_space(3)))
; __device__ __forceinline__ void transpose_item(Frame& F, const float* W, int K, int N, bf16* WT, int kb, int nb, const float* gk = nullptr) {
;     const int l = F.tid & 63, kg = F.tid >> 6, k0 = kb * 64, n0 = nb * 256;
;     const bool inb = (n0 + 4 * l) < N;
;     f32x4 v[2][4];
; #pragma unroll
;     for (int rep = 0; rep < 2; ++rep)
; #pragma unroll
;         for (int kk = 0; kk < 4; ++kk) v[rep][kk] = inb ? *(const f32x4*)(W + (size_t)(k0 + 4 * (kg + 8 * rep) + kk) * N + n0 + 4 * l) : (f32x4){0.f, 0.f, 0.f, 0.f};
;     if (gk) {
; #pragma unroll
;         for (int rep = 0; rep < 2; ++rep) { const f32x4 gg = *(const f32x4*)(gk + k0 + 4 * (kg + 8 * rep)); v[rep][0] = v[rep][0] * gg.x; v[rep][1] = v[rep][1] * gg.y; v[rep][2] = v[rep][2] * gg.z; v[rep][3] = v[rep][3] * gg.w; } }
; #pragma unroll
;     for (int rep = 0; rep < 2; ++rep) { const int kq = kg + 8 * rep;
; #pragma unroll
;         for (int i = 0; i < 4; ++i) { const int n = 4 * l + i; v2u w; w.x = pk2(v[rep][0][i], v[rep][1][i]); w.y = pk2(v[rep][2][i], v[rep][3][i]);
;             *(LAS v2u*)(F.lds + n * 128 + (((kq >> 1) ^ (l & 7)) * 16) + (kq & 1) * 8) = w; } }
;     __syncthreads();
; #pragma unroll
;     for (int q = 0; q < 4; ++q) { const int p = F.tid + 512 * q, n = p >> 3, j = p & 7;
;         const v4u d = *(const LAS v4u*)(F.lds + n * 128 + ((j ^ ((n >> 2) & 7)) * 16));
;         *(v4u*)(WT + (size_t)(n0 + n) * K + k0 + 8 * j) = d; }
;     __syncthreads();
; __device__ __forceinline__ void convert_weights(Frame& F, const int part, const int first, const int stride) {
;     ...
;         { const int l = l0 + r / I_DN; r %= I_DN; transpose_item(F, F.in[14] + (size_t)l * FF * D, FF, D, wdn + (size_t)l * D * FF, r / 8, r % 8); }
.LBB0_636:
	s_cmp_ge_i32 s8, s10
	s_mov_b64 s[14:15], -1
	s_cbranch_scc0 .LBB0_686
	s_add_i32 s85, s69, s8
	s_cmpk_gt_i32 s85, 0x13f
	s_cbranch_scc0 .LBB0_665
	s_add_i32 s92, s85, 0xfffffec0
	s_cmp_ge_i32 s92, s11
	s_cbranch_scc0 .LBB0_662
	s_add_i32 s18, s70, s8
	s_cmp_ge_i32 s18, s62
	s_cbranch_scc0 .LBB0_641
	v_mov_b64_e32 v[0:1], s[44:45]
	flat_load_dwordx2 v[0:1], v[0:1] offset:112
	s_add_i32 s12, s71, s8
	s_lshr_b32 s12, s12, 10
	s_add_i32 s26, s12, s9
	s_lshl_b64 s[12:13], s[26:27], 26
	v_lshlrev_b32_e32 v2, 2, v36
	v_mov_b32_e32 v3, v96
	s_waitcnt vmcnt(0) lgkmcnt(0)
	v_lshl_add_u64 v[0:1], v[0:1], 0, s[12:13]
	s_lshl_b64 s[12:13], s[26:27], 25
	s_add_u32 s14, s60, s12
	s_addc_u32 s15, s61, s13
	s_add_i32 s12, s72, s73
	s_and_b32 s40, s12, 0x1fc0
	s_and_b32 s19, s67, 0x700
	v_add_u32_e32 v12, s40, v38
	s_lshl_b32 s26, s19, 2
	v_lshl_add_u64 v[0:1], v[0:1], 0, s[26:27]
	v_ashrrev_i32_e32 v13, 31, v12
	v_lshl_add_u64 v[14:15], v[0:1], 0, v[2:3]
	v_lshlrev_b64 v[0:1], 13, v[12:13]
	v_lshl_add_u64 v[28:29], v[14:15], 0, v[0:1]
	s_mov_b32 s12, 0x40000
	v_add_co_u32_e32 v16, vcc, s12, v28
	s_mov_b32 s12, 0x42000
	s_nop 0
	v_addc_co_u32_e32 v17, vcc, 0, v29, vcc
	v_or_b32_e32 v4, 1, v12
	v_or_b32_e32 v8, 2, v12
	v_or_b32_e32 v12, 3, v12
	v_add_co_u32_e32 v20, vcc, s12, v28
	v_ashrrev_i32_e32 v5, 31, v4
	v_ashrrev_i32_e32 v9, 31, v8
	v_ashrrev_i32_e32 v13, 31, v12
	v_addc_co_u32_e32 v21, vcc, 0, v29, vcc
	s_mov_b32 s12, 0x44000
	v_lshlrev_b64 v[4:5], 13, v[4:5]
	v_lshlrev_b64 v[8:9], 13, v[8:9]
	v_lshlrev_b64 v[12:13], 13, v[12:13]
	v_add_co_u32_e32 v24, vcc, s12, v28
	v_lshl_add_u64 v[4:5], v[14:15], 0, v[4:5]
	v_lshl_add_u64 v[8:9], v[14:15], 0, v[8:9]
	v_lshl_add_u64 v[12:13], v[14:15], 0, v[12:13]
	v_addc_co_u32_e32 v25, vcc, 0, v29, vcc
	s_mov_b32 s12, 0x46000
	flat_load_dwordx4 v[0:3], v[28:29]
	v_add_co_u32_e32 v28, vcc, s12, v28
	flat_load_dwordx4 v[4:7], v[4:5]
	s_nop 0
	v_addc_co_u32_e32 v29, vcc, 0, v29, vcc
	flat_load_dwordx4 v[8:11], v[8:9]
	s_lshl_b32 s12, s40, 1
	flat_load_dwordx4 v[12:15], v[12:13]
	s_add_u32 s14, s14, s12
	flat_load_dwordx4 v[16:19], v[16:17]
	s_addc_u32 s15, s15, 0
	flat_load_dwordx4 v[20:23], v[20:21]
	flat_load_dwordx4 v[24:27], v[24:25]
	flat_load_dwordx4 v[28:31], v[28:29]
	s_waitcnt vmcnt(0) lgkmcnt(0)
	v_cvt_pk_bf16_f32 v32, v0, v4
	v_add_u32_e32 v4, v41, v37
	v_cvt_pk_bf16_f32 v0, v1, v5
	v_cvt_pk_bf16_f32 v33, v8, v12
	v_cvt_pk_bf16_f32 v1, v9, v13
	ds_write2_b64 v4, v[32:33], v[0:1] offset1:16
	v_cvt_pk_bf16_f32 v0, v2, v6
	v_cvt_pk_bf16_f32 v1, v10, v14
	v_cvt_pk_bf16_f32 v2, v3, v7
	v_cvt_pk_bf16_f32 v3, v11, v15
	ds_write2_b64 v4, v[0:1], v[2:3] offset0:32 offset1:48
	v_cvt_pk_bf16_f32 v0, v16, v20
	v_add_u32_e32 v4, v44, v37
	v_cvt_pk_bf16_f32 v2, v17, v21
	s_waitcnt vmcnt(0) lgkmcnt(0)
	v_cvt_pk_bf16_f32 v1, v24, v28
	v_cvt_pk_bf16_f32 v3, v25, v29
	ds_write2_b64 v4, v[0:1], v[2:3] offset1:16
	v_cvt_pk_bf16_f32 v0, v18, v22
	v_cvt_pk_bf16_f32 v1, v26, v30
	v_cvt_pk_bf16_f32 v2, v19, v23
	v_cvt_pk_bf16_f32 v3, v27, v31
	ds_write2_b64 v4, v[0:1], v[2:3] offset0:32 offset1:48
	v_add_u32_e32 v0, v46, v47
	s_waitcnt lgkmcnt(0)
	s_barrier
	ds_read_b128 v[2:5], v0
	v_add_u32_e32 v0, s19, v45
	v_ashrrev_i32_e32 v1, 31, v0
	v_lshlrev_b64 v[0:1], 14, v[0:1]
	v_lshl_add_u64 v[6:7], s[14:15], 0, v[0:1]
	v_lshlrev_b32_e32 v0, 1, v40
	v_mov_b32_e32 v1, v96
	v_lshl_add_u64 v[6:7], v[6:7], 0, v[0:1]
	s_waitcnt lgkmcnt(0)
	flat_store_dwordx4 v[6:7], v[2:5]
	v_add_u32_e32 v6, s19, v48
	v_ashrrev_i32_e32 v7, 31, v6
	v_add_u32_e32 v2, v49, v47
	ds_read_b128 v[2:5], v2
	v_lshlrev_b64 v[6:7], 14, v[6:7]
	v_lshl_add_u64 v[6:7], s[14:15], 0, v[6:7]
	v_lshl_add_u64 v[6:7], v[6:7], 0, v[0:1]
	s_waitcnt lgkmcnt(0)
	flat_store_dwordx4 v[6:7], v[2:5]
	v_add_u32_e32 v6, s19, v50
	s_nop 0
	v_add_u32_e32 v2, v51, v47
	ds_read_b128 v[2:5], v2
	v_ashrrev_i32_e32 v7, 31, v6
	v_lshlrev_b64 v[6:7], 14, v[6:7]
	v_lshl_add_u64 v[6:7], s[14:15], 0, v[6:7]
	v_lshl_add_u64 v[6:7], v[6:7], 0, v[0:1]
	s_waitcnt lgkmcnt(0)
	flat_store_dwordx4 v[6:7], v[2:5]
	v_add_u32_e32 v6, s19, v52
	v_ashrrev_i32_e32 v7, 31, v6
	v_add_u32_e32 v2, v53, v47
	ds_read_b128 v[2:5], v2
	v_lshlrev_b64 v[6:7], 14, v[6:7]
	v_lshl_add_u64 v[6:7], s[14:15], 0, v[6:7]
	v_lshl_add_u64 v[0:1], v[6:7], 0, v[0:1]
	s_mov_b64 s[14:15], 0
	s_waitcnt lgkmcnt(0)
	flat_store_dwordx4 v[0:1], v[2:5]
	s_waitcnt lgkmcnt(0)
	s_barrier

; __device__ __forceinline__ void transpose_item(Frame& F, const float* W, int K, int N, bf16* WT, int kb, int nb, const float* gk = nullptr) {
;     ...
;     if (gk) {
; #pragma unroll
;         for (int rep = 0; rep < 2; ++rep) { const f32x4 gg = *(const f32x4*)(gk + k0 + 4 * (kg + 8 * rep)); v[rep][0] = v[rep][0] * gg.x; v[rep][1] = v[rep][1] * gg.y; v[rep][2] = v[rep][2] * gg.z; v[rep][3] = v[rep][3] * gg.w; } }
; __device__ __forceinline__ void convert_weights(Frame& F, const int part, const int first, const int stride) {
;     ...
;         if (r < n_up) { const int l = l0 + r / I_UP; r %= I_UP; transpose_item(F, F.in[13] + (size_t)l * D * FF, D, FF, wup + (size_t)l * FF * D, r / 32, r % 32, F.in[12] + l * D); continue; } r -= n_up;
.LBB0_658:
	s_or_b64 exec, exec, s[18:19]
	v_cmp_ne_u64_e32 vcc, 0, v[4:5]
	s_ashr_i32 s51, s50, 31
	s_and_saveexec_b64 s[40:41], vcc
	s_cbranch_execz .LBB0_660
	s_lshl_b32 s12, s26, 11
	s_mov_b32 s13, s27
	v_lshl_add_u64 v[4:5], s[12:13], 2, v[4:5]
	v_lshl_add_u64 v[4:5], s[50:51], 2, v[4:5]
	v_lshl_add_u64 v[4:5], v[38:39], 2, v[4:5]
	flat_load_dwordx4 v[54:57], v[4:5]
	flat_load_dwordx4 v[58:61], v[4:5] offset:128
	s_waitcnt vmcnt(0) lgkmcnt(0)
	v_pk_mul_f32 v[8:9], v[8:9], v[54:55] op_sel_hi:[1,0]
	v_pk_mul_f32 v[6:7], v[6:7], v[54:55] op_sel_hi:[1,0]
	v_pk_mul_f32 v[2:3], v[2:3], v[54:55] op_sel:[0,1]
	v_pk_mul_f32 v[0:1], v[0:1], v[54:55] op_sel:[0,1]
	v_pk_mul_f32 v[12:13], v[12:13], v[56:57] op_sel_hi:[1,0]
	v_pk_mul_f32 v[10:11], v[10:11], v[56:57] op_sel_hi:[1,0]
	v_mov_b32_e32 v34, v57
	v_pk_mul_f32 v[16:17], v[16:17], v[34:35] op_sel_hi:[1,0]
	v_pk_mul_f32 v[14:15], v[14:15], v[34:35] op_sel_hi:[1,0]
	s_waitcnt vmcnt(0) lgkmcnt(0)
	v_mov_b32_e32 v4, v61
	v_pk_mul_f32 v[20:21], v[20:21], v[58:59] op_sel_hi:[1,0]
	v_pk_mul_f32 v[18:19], v[18:19], v[58:59] op_sel_hi:[1,0]
	v_pk_mul_f32 v[24:25], v[24:25], v[58:59] op_sel:[0,1]
	v_pk_mul_f32 v[22:23], v[22:23], v[58:59] op_sel:[0,1]
	v_pk_mul_f32 v[28:29], v[28:29], v[60:61] op_sel_hi:[1,0]
	v_pk_mul_f32 v[26:27], v[26:27], v[60:61] op_sel_hi:[1,0]
	v_pk_mul_f32 v[32:33], v[32:33], v[4:5] op_sel_hi:[1,0]
	v_pk_mul_f32 v[30:31], v[30:31], v[4:5] op_sel_hi:[1,0]

; #define LAS __attribute__((address_space(3)))
; __device__ __forceinline__ void transpose_item(Frame& F, const float* W, int K, int N, bf16* WT, int kb, int nb, const float* gk = nullptr) {
;     const int l = F.tid & 63, kg = F.tid >> 6, k0 = kb * 64, n0 = nb * 256;
;     const bool inb = (n0 + 4 * l) < N;
;     f32x4 v[2][4];
; #pragma unroll
;     for (int rep = 0; rep < 2; ++rep)
; #pragma unroll
;         for (int kk = 0; kk < 4; ++kk) v[rep][kk] = inb ? *(const f32x4*)(W + (size_t)(k0 + 4 * (kg + 8 * rep) + kk) * N + n0 + 4 * l) : (f32x4){0.f, 0.f, 0.f, 0.f};
;     if (gk) {
; #pragma unroll
;         for (int rep = 0; rep < 2; ++rep) { const f32x4 gg = *(const f32x4*)(gk + k0 + 4 * (kg + 8 * rep)); v[rep][0] = v[rep][0] * gg.x; v[rep][1] = v[rep][1] * gg.y; v[rep][2] = v[rep][2] * gg.z; v[rep][3] = v[rep][3] * gg.w; } }
; #pragma unroll
;     for (int rep = 0; rep < 2; ++rep) { const int kq = kg + 8 * rep;
; #pragma unroll
;         for (int i = 0; i < 4; ++i) { const int n = 4 * l + i; v2u w; w.x = pk2(v[rep][0][i], v[rep][1][i]); w.y = pk2(v[rep][2][i], v[rep][3][i]);
;             *(LAS v2u*)(F.lds + n * 128 + (((kq >> 1) ^ (l & 7)) * 16) + (kq & 1) * 8) = w; } }
;     __syncthreads();
; #pragma unroll
;     for (int q = 0; q < 4; ++q) { const int p = F.tid + 512 * q, n = p >> 3, j = p & 7;
;         const v4u d = *(const LAS v4u*)(F.lds + n * 128 + ((j ^ ((n >> 2) & 7)) * 16));
;         *(v4u*)(WT + (size_t)(n0 + n) * K + k0 + 8 * j) = d; }
;     __syncthreads();
; __device__ __forceinline__ void convert_weights(Frame& F, const int part, const int first, const int stride) {
;     ...
;         if (r < n_out) { const int l = l0 + r / I_OUT; r %= I_OUT; transpose_item(F, F.in[11] + (size_t)l * D * D, D, D, wout + (size_t)l * D * D, r / 8, r % 8); continue; } r -= n_out;
.LBB0_662:
	s_andn2_b64 vcc, exec, s[14:15]
	s_cbranch_vccnz .LBB0_664
	v_mov_b64_e32 v[0:1], s[44:45]
	flat_load_dwordx2 v[0:1], v[0:1] offset:88
	s_lshr_b32 s12, s92, 8
	s_add_i32 s26, s12, s9
	s_lshl_b64 s[12:13], s[26:27], 24
	v_lshlrev_b32_e32 v2, 2, v36
	v_mov_b32_e32 v3, v96
	s_waitcnt vmcnt(0) lgkmcnt(0)
	v_lshl_add_u64 v[0:1], v[0:1], 0, s[12:13]
	s_lshl_b64 s[12:13], s[26:27], 23
	s_add_u32 s14, s53, s12
	s_addc_u32 s15, s57, s13
	s_add_i32 s12, s73, 0xfffff600
	s_and_b32 s19, s12, 0x7c0
	s_and_b32 s18, s67, 0x700
	v_add_u32_e32 v12, s19, v38
	s_lshl_b32 s26, s18, 2
	v_lshl_add_u64 v[0:1], v[0:1], 0, s[26:27]
	v_ashrrev_i32_e32 v13, 31, v12
	v_lshl_add_u64 v[14:15], v[0:1], 0, v[2:3]
	v_lshlrev_b64 v[0:1], 13, v[12:13]
	v_lshl_add_u64 v[28:29], v[14:15], 0, v[0:1]
	s_mov_b32 s12, 0x40000
	v_add_co_u32_e32 v16, vcc, s12, v28
	s_mov_b32 s12, 0x42000
	s_nop 0
	v_addc_co_u32_e32 v17, vcc, 0, v29, vcc
	v_or_b32_e32 v4, 1, v12
	v_or_b32_e32 v8, 2, v12
	v_or_b32_e32 v12, 3, v12
	v_add_co_u32_e32 v20, vcc, s12, v28
	v_ashrrev_i32_e32 v5, 31, v4
	v_ashrrev_i32_e32 v9, 31, v8
	v_ashrrev_i32_e32 v13, 31, v12
	v_addc_co_u32_e32 v21, vcc, 0, v29, vcc
	s_mov_b32 s12, 0x44000
	v_lshlrev_b64 v[4:5], 13, v[4:5]
	v_lshlrev_b64 v[8:9], 13, v[8:9]
	v_lshlrev_b64 v[12:13], 13, v[12:13]
	v_add_co_u32_e32 v24, vcc, s12, v28
	v_lshl_add_u64 v[4:5], v[14:15], 0, v[4:5]
	v_lshl_add_u64 v[8:9], v[14:15], 0, v[8:9]
	v_lshl_add_u64 v[12:13], v[14:15], 0, v[12:13]
	v_addc_co_u32_e32 v25, vcc, 0, v29, vcc
	s_mov_b32 s12, 0x46000
	flat_load_dwordx4 v[0:3], v[28:29]
	v_add_co_u32_e32 v28, vcc, s12, v28
	flat_load_dwordx4 v[4:7], v[4:5]
	s_nop 0
	v_addc_co_u32_e32 v29, vcc, 0, v29, vcc
	flat_load_dwordx4 v[8:11], v[8:9]
	s_lshl_b32 s12, s19, 1
	flat_load_dwordx4 v[12:15], v[12:13]
	s_add_u32 s14, s14, s12
	flat_load_dwordx4 v[16:19], v[16:17]
	s_addc_u32 s15, s15, 0
	flat_load_dwordx4 v[20:23], v[20:21]
	flat_load_dwordx4 v[24:27], v[24:25]
	flat_load_dwordx4 v[28:31], v[28:29]
	s_waitcnt vmcnt(0) lgkmcnt(0)
	v_cvt_pk_bf16_f32 v32, v0, v4
	v_add_u32_e32 v4, v41, v37
	v_cvt_pk_bf16_f32 v0, v1, v5
	v_cvt_pk_bf16_f32 v33, v8, v12
	v_cvt_pk_bf16_f32 v1, v9, v13
	ds_write2_b64 v4, v[32:33], v[0:1] offset1:16
	v_cvt_pk_bf16_f32 v0, v2, v6
	v_cvt_pk_bf16_f32 v1, v10, v14
	v_cvt_pk_bf16_f32 v2, v3, v7
	v_cvt_pk_bf16_f32 v3, v11, v15
	ds_write2_b64 v4, v[0:1], v[2:3] offset0:32 offset1:48
	v_cvt_pk_bf16_f32 v0, v16, v20
	v_add_u32_e32 v4, v44, v37
	v_cvt_pk_bf16_f32 v2, v17, v21
	s_waitcnt vmcnt(0) lgkmcnt(0)
	v_cvt_pk_bf16_f32 v1, v24, v28
	v_cvt_pk_bf16_f32 v3, v25, v29
	ds_write2_b64 v4, v[0:1], v[2:3] offset1:16
	v_cvt_pk_bf16_f32 v0, v18, v22
	v_cvt_pk_bf16_f32 v1, v26, v30
	v_cvt_pk_bf16_f32 v2, v19, v23
	v_cvt_pk_bf16_f32 v3, v27, v31
	ds_write2_b64 v4, v[0:1], v[2:3] offset0:32 offset1:48
	v_add_u32_e32 v0, v46, v47
	s_waitcnt lgkmcnt(0)
	s_barrier
	ds_read_b128 v[2:5], v0
	v_add_u32_e32 v0, s18, v45
	v_ashrrev_i32_e32 v1, 31, v0
	v_lshlrev_b64 v[0:1], 12, v[0:1]
	v_lshl_add_u64 v[6:7], s[14:15], 0, v[0:1]
	v_lshlrev_b32_e32 v0, 1, v40
	v_mov_b32_e32 v1, v96
	v_lshl_add_u64 v[6:7], v[6:7], 0, v[0:1]
	s_waitcnt lgkmcnt(0)
	flat_store_dwordx4 v[6:7], v[2:5]
	v_add_u32_e32 v6, s18, v48
	v_ashrrev_i32_e32 v7, 31, v6
	v_add_u32_e32 v2, v49, v47
	ds_read_b128 v[2:5], v2
	v_lshlrev_b64 v[6:7], 12, v[6:7]
	v_lshl_add_u64 v[6:7], s[14:15], 0, v[6:7]
	v_lshl_add_u64 v[6:7], v[6:7], 0, v[0:1]
	s_waitcnt lgkmcnt(0)
	flat_store_dwordx4 v[6:7], v[2:5]
	v_add_u32_e32 v6, s18, v50
	s_nop 0
	v_add_u32_e32 v2, v51, v47
	ds_read_b128 v[2:5], v2
	v_ashrrev_i32_e32 v7, 31, v6
	v_lshlrev_b64 v[6:7], 12, v[6:7]
	v_lshl_add_u64 v[6:7], s[14:15], 0, v[6:7]
	v_lshl_add_u64 v[6:7], v[6:7], 0, v[0:1]
	s_waitcnt lgkmcnt(0)
	flat_store_dwordx4 v[6:7], v[2:5]
	v_add_u32_e32 v6, s18, v52
	v_ashrrev_i32_e32 v7, 31, v6
	v_add_u32_e32 v2, v53, v47
	ds_read_b128 v[2:5], v2
	v_lshlrev_b64 v[6:7], 12, v[6:7]
	v_lshl_add_u64 v[6:7], s[14:15], 0, v[6:7]
	v_lshl_add_u64 v[0:1], v[6:7], 0, v[0:1]
	s_waitcnt lgkmcnt(0)
	flat_store_dwordx4 v[0:1], v[2:5]
	s_waitcnt lgkmcnt(0)
	s_barrier

; __device__ __forceinline__ void transpose_item(Frame& F, const float* W, int K, int N, bf16* WT, int kb, int nb, const float* gk = nullptr) {
;     ...
;     if (gk) {
; #pragma unroll
;         for (int rep = 0; rep < 2; ++rep) { const f32x4 gg = *(const f32x4*)(gk + k0 + 4 * (kg + 8 * rep)); v[rep][0] = v[rep][0] * gg.x; v[rep][1] = v[rep][1] * gg.y; v[rep][2] = v[rep][2] * gg.z; v[rep][3] = v[rep][3] * gg.w; } }
; __device__ __forceinline__ void convert_weights(Frame& F, const int part, const int first, const int stride) {
;     ...
;         if (r < n_swa) { const int l = part - 1; transpose_item(F, F.in[8] + (size_t)l * D * SWA_IN, D, SWA_IN, wswa + (size_t)l * SWA_NP * D, r / 10, r % 10, F.in[3] + (2 * l + 1) * D); continue; } r -= n_swa;
.LBB0_682:
	s_or_b64 exec, exec, s[18:19]
	v_lshl_add_u64 v[32:33], s[4:5], 2, v[32:33]
	s_mov_b64 s[12:13], 0x2000
	v_lshl_add_u64 v[32:33], v[32:33], 0, s[12:13]
	v_cmp_ne_u64_e32 vcc, 0, v[32:33]
	s_ashr_i32 s41, s40, 31
	s_and_saveexec_b64 s[50:51], vcc
	s_cbranch_execz .LBB0_684
	v_lshl_add_u64 v[32:33], s[40:41], 2, v[32:33]
	v_lshl_add_u64 v[42:43], v[38:39], 2, v[32:33]
	flat_load_dwordx4 v[32:35], v[42:43]
	flat_load_dwordx4 v[58:61], v[42:43] offset:128
	s_waitcnt vmcnt(0) lgkmcnt(0)
	v_pk_mul_f32 v[6:7], v[6:7], v[32:33] op_sel_hi:[1,0]
	v_pk_mul_f32 v[4:5], v[4:5], v[32:33] op_sel_hi:[1,0]
	v_pk_mul_f32 v[2:3], v[2:3], v[32:33] op_sel:[0,1]
	v_pk_mul_f32 v[0:1], v[0:1], v[32:33] op_sel:[0,1]
	v_mov_b32_e32 v32, v35
	v_pk_mul_f32 v[10:11], v[10:11], v[34:35] op_sel_hi:[1,0]
	v_pk_mul_f32 v[8:9], v[8:9], v[34:35] op_sel_hi:[1,0]
	v_pk_mul_f32 v[14:15], v[14:15], v[32:33] op_sel_hi:[1,0]
	v_pk_mul_f32 v[12:13], v[12:13], v[32:33] op_sel_hi:[1,0]
	s_waitcnt vmcnt(0) lgkmcnt(0)
	v_pk_mul_f32 v[18:19], v[18:19], v[58:59] op_sel_hi:[1,0]
	v_pk_mul_f32 v[16:17], v[16:17], v[58:59] op_sel_hi:[1,0]
	v_pk_mul_f32 v[22:23], v[22:23], v[58:59] op_sel:[0,1]
	v_pk_mul_f32 v[20:21], v[20:21], v[58:59] op_sel:[0,1]
	v_mov_b32_e32 v58, v61
	v_pk_mul_f32 v[26:27], v[26:27], v[60:61] op_sel_hi:[1,0]
	v_pk_mul_f32 v[24:25], v[24:25], v[60:61] op_sel_hi:[1,0]
	v_pk_mul_f32 v[30:31], v[30:31], v[58:59] op_sel_hi:[1,0]
	v_pk_mul_f32 v[28:29], v[28:29], v[58:59] op_sel_hi:[1,0]

; __device__ __forceinline__ void transpose_item(Frame& F, const float* W, int K, int N, bf16* WT, int kb, int nb, const float* gk = nullptr) {
;     ...
;     if (gk) {
; #pragma unroll
;         for (int rep = 0; rep < 2; ++rep) { const f32x4 gg = *(const f32x4*)(gk + k0 + 4 * (kg + 8 * rep)); v[rep][0] = v[rep][0] * gg.x; v[rep][1] = v[rep][1] * gg.y; v[rep][2] = v[rep][2] * gg.z; v[rep][3] = v[rep][3] * gg.w; } }
; __device__ __forceinline__ void convert_weights(Frame& F, const int part, const int first, const int stride) {
;     ...
;         if (r < n_gla) { const int l = part; transpose_item(F, F.in[4] + (size_t)l * D * GLA_IN, D, GLA_IN, wgla + (size_t)l * GLA_NP * D, r / 23, r % 23, F.in[3] + (2 * l) * D); continue; } r -= n_gla;
.LBB0_703:
	s_or_b64 exec, exec, s[18:19]
	v_cmp_ne_u64_e32 vcc, 0, v[32:33]
	s_ashr_i32 s41, s40, 31
	s_and_saveexec_b64 s[50:51], vcc
	s_cbranch_execz .LBB0_634
	v_lshl_add_u64 v[32:33], s[48:49], 2, v[32:33]
	v_lshl_add_u64 v[32:33], s[40:41], 2, v[32:33]
	v_lshl_add_u64 v[42:43], v[38:39], 2, v[32:33]
	flat_load_dwordx4 v[32:35], v[42:43]
	flat_load_dwordx4 v[58:61], v[42:43] offset:128
	s_waitcnt vmcnt(0) lgkmcnt(0)
	v_pk_mul_f32 v[6:7], v[6:7], v[32:33] op_sel_hi:[1,0]
	v_pk_mul_f32 v[4:5], v[4:5], v[32:33] op_sel_hi:[1,0]
	v_pk_mul_f32 v[2:3], v[2:3], v[32:33] op_sel:[0,1]
	v_pk_mul_f32 v[0:1], v[0:1], v[32:33] op_sel:[0,1]
	v_mov_b32_e32 v32, v35
	v_pk_mul_f32 v[10:11], v[10:11], v[34:35] op_sel_hi:[1,0]
	v_pk_mul_f32 v[8:9], v[8:9], v[34:35] op_sel_hi:[1,0]
	v_pk_mul_f32 v[14:15], v[14:15], v[32:33] op_sel_hi:[1,0]
	v_pk_mul_f32 v[12:13], v[12:13], v[32:33] op_sel_hi:[1,0]
	s_waitcnt vmcnt(0) lgkmcnt(0)
	v_pk_mul_f32 v[18:19], v[18:19], v[58:59] op_sel_hi:[1,0]
	v_pk_mul_f32 v[16:17], v[16:17], v[58:59] op_sel_hi:[1,0]
	v_pk_mul_f32 v[22:23], v[22:23], v[58:59] op_sel:[0,1]
	v_pk_mul_f32 v[20:21], v[20:21], v[58:59] op_sel:[0,1]
	v_mov_b32_e32 v58, v61
	v_pk_mul_f32 v[26:27], v[26:27], v[60:61] op_sel_hi:[1,0]
	v_pk_mul_f32 v[24:25], v[24:25], v[60:61] op_sel_hi:[1,0]
	v_pk_mul_f32 v[30:31], v[30:31], v[58:59] op_sel_hi:[1,0]
	v_pk_mul_f32 v[28:29], v[28:29], v[58:59] op_sel_hi:[1,0]
	s_branch .LBB0_634

; __device__ __forceinline__ void gla_scan_item(Frame& F, const int sitem) {
;     const int sixth = sitem % 6, hh = (sitem / 6) & 3, b = sitem / 24;
;     const bf16* QIN = (const bf16*)(F.ws + WS_QIN); const bf16* KOT = (const bf16*)(F.ws + WS_KOT); const bf16* VT = (const bf16*)(F.ws + WS_VT); const bf16* GA = (const bf16*)(F.ws + WS_GA);
;     const float* DEC = (const float*)(F.ws + WS_DEC); bf16* ORAW = (bf16*)(F.ws + WS_ORAW);
;     constexpr int QP = 528, TP = 144;
;     const ldsp Qs = F.lds, Kt = F.lds + 33792, As = F.lds + 70656, Vs = F.lds + 79872, Dc = F.lds + 89088, Xs = F.lds + 90112;
;     const int tid = F.tid, lane = F.lane, r = lane & 31, h = lane >> 5, w = F.wave, dvs = w & 1, dkq = w >> 1;
;     const unsigned oq = (unsigned)((tid >> 5) * 1024 + 8 * (tid & 31)), o8 = (unsigned)(8 * tid), od = (unsigned)(4 * tid);
;     v4u rq[4], rk[4], ra, rv, rd = (v4u){0u, 0u, 0u, 0u};
;     ...
;     f32x16 S[2];
; #pragma unroll
;     for (int kt = 0; kt < 2; ++kt)
; #pragma unroll
;         for (int i = 0; i < 16; ++i) S[kt][i] = 0.f;
;     GLA_LOAD(0);
.LBB0_706:
	s_and_b64 vcc, exec, s[0:1]
	s_cbranch_vccz .LBB0_729
	s_and_b32 s0, s56, 7
	s_lshr_b32 s1, s56, 3
	s_mul_i32 s0, s0, 12
	s_add_i32 s56, s0, s1
	s_mul_hi_i32 s0, s56, 0x2aaaaaab
	s_lshr_b32 s1, s0, 31
	s_add_i32 s8, s0, s1
	s_and_b32 s12, s8, 3
	s_add_u32 s4, s42, 0x2d700000
	s_addc_u32 s5, s43, 0
	s_add_u32 s44, s42, 0x30f00000
	s_addc_u32 s45, s43, 0
	s_mul_i32 s8, s8, 6
	s_ashr_i32 s0, s0, 2
	s_sub_i32 s40, s56, s8
	s_add_i32 s48, s0, s1
	s_add_u32 s46, s42, 0x2b700000
	s_addc_u32 s47, s43, 0
	s_lshl_b32 s13, s48, 8
	s_ashr_i32 s49, s48, 31
	s_or_b32 s50, s13, s12
	s_lshl_b64 s[14:15], s[48:49], 23
	s_add_u32 s0, s42, s14
	v_and_b32_e32 v6, 31, v163
	s_addc_u32 s1, s43, s15
	s_lshl_b32 s26, s12, 9
	v_ashrrev_i32_e32 v7, 5, v163
	v_lshlrev_b32_e32 v0, 3, v6
	s_add_u32 s8, s0, s26
	v_lshl_or_b32 v0, v7, 10, v0
	s_addc_u32 s9, s1, 0
	s_waitcnt lgkmcnt(0)
	v_mov_b32_e32 v1, v96
	s_ashr_i32 s51, s50, 31
	s_lshl_b32 s0, s40, 6
	v_lshl_add_u64 v[4:5], v[0:1], 1, s[8:9]
	s_brev_b32 s8, 44
	s_lshl_b64 s[10:11], s[50:51], 15
	s_lshl_b64 s[18:19], s[50:51], 13
	s_mul_i32 s52, s50, 0x180
	s_ashr_i32 s1, s0, 31
	v_add_co_u32_e32 v8, vcc, s8, v4
	s_mul_hi_i32 s41, s50, 0x180
	s_add_u32 s40, s52, s0
	v_addc_co_u32_e32 v9, vcc, 0, v5, vcc
	s_mov_b32 s8, 0x34008000
	s_addc_u32 s41, s41, s1
	v_add_co_u32_e32 v10, vcc, s8, v4
	s_lshl_b64 s[40:41], s[40:41], 7
	s_nop 0
	v_addc_co_u32_e32 v11, vcc, 0, v5, vcc
	s_mov_b32 s8, 0x34010000
	s_waitcnt vmcnt(0)
	flat_load_dwordx4 v[80:83], v[8:9]
	flat_load_dwordx4 v[84:87], v[10:11]
	v_add_co_u32_e32 v8, vcc, s8, v4
	s_add_u32 s52, s42, 0x30700000
	s_nop 0
	v_addc_co_u32_e32 v9, vcc, 0, v5, vcc
	s_mov_b32 s8, 0x34018000
	s_addc_u32 s53, s43, 0
	v_lshlrev_b32_e32 v2, 3, v163
	v_add_co_u32_e32 v4, vcc, s8, v4
	s_add_u32 s8, s46, s10
	v_mov_b32_e32 v3, v96
	v_addc_co_u32_e32 v5, vcc, 0, v5, vcc
	s_addc_u32 s9, s47, s11
	v_lshlrev_b64 v[2:3], 1, v[2:3]
	flat_load_dwordx4 v[88:91], v[8:9]
	flat_load_dwordx4 v[92:95], v[4:5]
	v_lshl_add_u64 v[4:5], s[8:9], 0, v[2:3]
	v_add_co_u32_e32 v8, vcc, s3, v4
	s_movk_i32 s8, 0x4000
	s_nop 0
	v_addc_co_u32_e32 v9, vcc, 0, v5, vcc
	s_add_u32 s10, s4, s40
	flat_load_dwordx4 v[100:103], v[4:5]
	flat_load_dwordx4 v[104:107], v[8:9]
	v_add_co_u32_e32 v8, vcc, s8, v4
	s_addc_u32 s11, s5, s41
	s_nop 0
	v_addc_co_u32_e32 v9, vcc, 0, v5, vcc
	s_movk_i32 s8, 0x6000
	v_add_co_u32_e32 v4, vcc, s8, v4
	s_add_u32 s8, s52, s18
	s_nop 0
	v_addc_co_u32_e32 v5, vcc, 0, v5, vcc
	s_addc_u32 s9, s53, s19
	flat_load_dwordx4 v[112:115], v[8:9]
	flat_load_dwordx4 v[116:119], v[4:5]
	v_lshl_add_u64 v[4:5], s[8:9], 0, v[2:3]
	v_lshl_add_u64 v[8:9], s[10:11], 0, v[2:3]
	flat_load_dwordx4 v[120:123], v[4:5]
	flat_load_dwordx4 v[124:127], v[8:9]
	v_lshlrev_b32_e32 v4, 2, v163
	v_cmp_gt_i32_e64 s[40:41], 64, v163
	v_cmp_lt_i32_e32 vcc, 63, v163
	v_mov_b32_e32 v5, v96
	s_and_saveexec_b64 s[8:9], vcc
	s_xor_b64 s[18:19], exec, s[8:9]
	s_or_saveexec_b64 s[18:19], s[18:19]
	v_mov_b32_e32 v98, v96
	v_mov_b32_e32 v99, v96
	v_mov_b32_e32 v97, v96
	v_mov_b64_e32 v[110:111], v[98:99]
	v_mov_b64_e32 v[108:109], v[96:97]
	s_xor_b64 exec, exec, s[18:19]
	s_cbranch_execz .LBB0_709
	s_lshl_b64 s[8:9], s[50:51], 10
	s_add_u32 s8, s44, s8
	s_addc_u32 s9, s45, s9
	v_lshl_add_u64 v[8:9], v[4:5], 2, s[8:9]
	flat_load_dwordx4 v[108:111], v[8:9]
